# speedup vs baseline: 1.0033x; 1.0033x over previous
; #define tidx() tidx_(wv_)
; __device__ __forceinline__ float* outp(unsigned char* ws) { return (float*)inp(ws, 33); }
; __device__ __forceinline__ void final_norm(unsigned char* ws, int wv_) {
;   const float* ss = (const float*)(ws + OFF_SS) + 8 * T_;
;   const float* g = inp(ws, 32);
;   float* x = outp(ws);
;   int wave = tidx() >> 6, lane = tidx() & 63;
;   for (int row = bidx() * 8 + wave; row < T_; row += gridDim.x * 8) {
;     float s = rsqrtf(ss[row] * (1.f / D_) + 1e-6f);
;     for (int i = 0; i < 8; ++i) {
;       int col = (i * 64 + lane) * 4;
;       float4 v = *(float4*)(x + (size_t)row * D_ + col);
;       float4 gg = *(const float4*)(g + col);
;       v.x *= s * gg.x; v.y *= s * gg.y; v.z *= s * gg.z; v.w *= s * gg.w;
;       *(float4*)(x + (size_t)row * D_ + col) = v;
;     }
;   }
; }
.LBB0_1551:
	s_waitcnt vmcnt(0)
	v_mbcnt_lo_u32_b32 v0, -1, 0
	v_mbcnt_hi_u32_b32 v0, -1, v0
	v_readlane_b32 s2, v251, 14
	v_or_b32_e32 v0, s63, v0
	v_ashrrev_i32_e32 v0, 6, v0
	v_add_u32_e32 v0, s2, v0
	s_movk_i32 s2, 0x2000
	v_cmp_gt_i32_e32 vcc, s2, v0
	v_mbcnt_lo_u32_b32 v1, -1, 0
	v_mbcnt_hi_u32_b32 v1, -1, v1
	s_and_saveexec_b64 s[2:3], vcc
	s_cbranch_execz .LBB0_1554
	s_load_dwordx4 s[4:7], s[0:1], 0x100
	v_lshlrev_b32_e32 v2, 4, v1
	v_mov_b32_e32 v3, 0
	v_readfirstlane_b32 s17, v0
	s_add_u32 s10, s78, 0x2b180000
	s_addc_u32 s11, s79, 0
	s_lshl_b32 s8, s39, 3
	v_mov_b32_e32 v22, 0x358637bd
	s_mov_b32 s16, 0x800000
	s_waitcnt lgkmcnt(0)
	s_add_u32 s12, s4, 0x1000
	s_addc_u32 s13, s5, 0
	global_load_dwordx4 v[48:51], v2, s[4:5]
	global_load_dwordx4 v[52:55], v2, s[4:5] offset:1024
	global_load_dwordx4 v[56:59], v2, s[4:5] offset:2048
	global_load_dwordx4 v[60:63], v2, s[4:5] offset:3072
	global_load_dwordx4 v[64:67], v2, s[12:13]
	global_load_dwordx4 v[68:71], v2, s[12:13] offset:1024
	global_load_dwordx4 v[72:75], v2, s[12:13] offset:2048
	global_load_dwordx4 v[76:79], v2, s[12:13] offset:3072
	s_cmp_eq_u32 s39, 0x100
	s_cbranch_scc0 .Lfn_loop
	s_mov_b32 s22, s17
	s_lshl_b32 s23, s22, 2
	v_mov_b32_e32 v4, s23
	s_lshr_b32 s41, s22, 19
	s_lshl_b32 s40, s22, 13
	s_add_u32 s40, s6, s40
	s_addc_u32 s41, s7, s41
	s_add_u32 s42, s40, 0x1000
	s_addc_u32 s43, s41, 0
	global_load_dword v24, v4, s[10:11]
	global_load_dwordx4 v[80:83], v2, s[40:41]
	global_load_dwordx4 v[84:87], v2, s[40:41] offset:1024
	global_load_dwordx4 v[88:91], v2, s[40:41] offset:2048
	global_load_dwordx4 v[92:95], v2, s[40:41] offset:3072
	global_load_dwordx4 v[96:99], v2, s[42:43]
	global_load_dwordx4 v[100:103], v2, s[42:43] offset:1024
	global_load_dwordx4 v[104:107], v2, s[42:43] offset:2048
	global_load_dwordx4 v[108:111], v2, s[42:43] offset:3072
	s_add_i32 s22, s17, 0x800
	s_lshl_b32 s23, s22, 2
	v_mov_b32_e32 v5, s23
	s_lshr_b32 s45, s22, 19
	s_lshl_b32 s44, s22, 13
	s_add_u32 s44, s6, s44
	s_addc_u32 s45, s7, s45
	s_add_u32 s46, s44, 0x1000
	s_addc_u32 s47, s45, 0
	global_load_dword v25, v5, s[10:11]
	global_load_dwordx4 v[112:115], v2, s[44:45]
	global_load_dwordx4 v[116:119], v2, s[44:45] offset:1024
	global_load_dwordx4 v[120:123], v2, s[44:45] offset:2048
	global_load_dwordx4 v[124:127], v2, s[44:45] offset:3072
	global_load_dwordx4 v[128:131], v2, s[46:47]
	global_load_dwordx4 v[132:135], v2, s[46:47] offset:1024
	global_load_dwordx4 v[136:139], v2, s[46:47] offset:2048
	global_load_dwordx4 v[140:143], v2, s[46:47] offset:3072
	s_add_i32 s22, s17, 0x1000
	s_lshl_b32 s23, s22, 2
	v_mov_b32_e32 v14, s23
	s_lshr_b32 s49, s22, 19
	s_lshl_b32 s48, s22, 13
	s_add_u32 s48, s6, s48
	s_addc_u32 s49, s7, s49
	s_add_u32 s50, s48, 0x1000
	s_addc_u32 s51, s49, 0
	global_load_dword v26, v14, s[10:11]
	global_load_dwordx4 v[144:147], v2, s[48:49]
	global_load_dwordx4 v[148:151], v2, s[48:49] offset:1024
	global_load_dwordx4 v[152:155], v2, s[48:49] offset:2048
	global_load_dwordx4 v[156:159], v2, s[48:49] offset:3072
	global_load_dwordx4 v[160:163], v2, s[50:51]
	global_load_dwordx4 v[164:167], v2, s[50:51] offset:1024
	global_load_dwordx4 v[168:171], v2, s[50:51] offset:2048
	global_load_dwordx4 v[172:175], v2, s[50:51] offset:3072
	s_add_i32 s22, s17, 0x1800
	s_lshl_b32 s23, s22, 2
	v_mov_b32_e32 v15, s23
	s_lshr_b32 s53, s22, 19
	s_lshl_b32 s52, s22, 13
	s_add_u32 s52, s6, s52
	s_addc_u32 s53, s7, s53
	s_add_u32 s54, s52, 0x1000
	s_addc_u32 s55, s53, 0
	global_load_dword v27, v15, s[10:11]
	global_load_dwordx4 v[176:179], v2, s[52:53]
	global_load_dwordx4 v[180:183], v2, s[52:53] offset:1024
	global_load_dwordx4 v[184:187], v2, s[52:53] offset:2048
	global_load_dwordx4 v[188:191], v2, s[52:53] offset:3072
	global_load_dwordx4 v[192:195], v2, s[54:55]
	global_load_dwordx4 v[196:199], v2, s[54:55] offset:1024
	global_load_dwordx4 v[200:203], v2, s[54:55] offset:2048
	global_load_dwordx4 v[204:207], v2, s[54:55] offset:3072
	s_waitcnt vmcnt(27)
	v_fmamk_f32 v7, v24, 0x3a000000, v22
	v_mul_f32_e32 v8, 0x4b800000, v7
	v_cmp_gt_f32_e32 vcc, s16, v7
	s_nop 1
	v_cndmask_b32_e32 v7, v7, v8, vcc
	v_rsq_f32_e32 v7, v7
	s_nop 0
	v_mul_f32_e32 v8, 0x45800000, v7
	v_cndmask_b32_e32 v40, v7, v8, vcc
	s_nop 0
	v_pk_mul_f32 v[10:11], v[48:49], v[40:41] op_sel_hi:[1,0]
	v_pk_mul_f32 v[12:13], v[50:51], v[40:41] op_sel_hi:[1,0]
	v_pk_mul_f32 v[80:81], v[80:81], v[10:11]
	v_pk_mul_f32 v[82:83], v[82:83], v[12:13]
	v_pk_mul_f32 v[10:11], v[52:53], v[40:41] op_sel_hi:[1,0]
	v_pk_mul_f32 v[12:13], v[54:55], v[40:41] op_sel_hi:[1,0]
	v_pk_mul_f32 v[84:85], v[84:85], v[10:11]
	v_pk_mul_f32 v[86:87], v[86:87], v[12:13]
	v_pk_mul_f32 v[10:11], v[56:57], v[40:41] op_sel_hi:[1,0]
	v_pk_mul_f32 v[12:13], v[58:59], v[40:41] op_sel_hi:[1,0]
	v_pk_mul_f32 v[88:89], v[88:89], v[10:11]
	v_pk_mul_f32 v[90:91], v[90:91], v[12:13]
	v_pk_mul_f32 v[10:11], v[60:61], v[40:41] op_sel_hi:[1,0]
	v_pk_mul_f32 v[12:13], v[62:63], v[40:41] op_sel_hi:[1,0]
	v_pk_mul_f32 v[92:93], v[92:93], v[10:11]
	v_pk_mul_f32 v[94:95], v[94:95], v[12:13]
	v_pk_mul_f32 v[10:11], v[64:65], v[40:41] op_sel_hi:[1,0]
	v_pk_mul_f32 v[12:13], v[66:67], v[40:41] op_sel_hi:[1,0]
	v_pk_mul_f32 v[96:97], v[96:97], v[10:11]
	v_pk_mul_f32 v[98:99], v[98:99], v[12:13]
	v_pk_mul_f32 v[10:11], v[68:69], v[40:41] op_sel_hi:[1,0]
	v_pk_mul_f32 v[12:13], v[70:71], v[40:41] op_sel_hi:[1,0]
	v_pk_mul_f32 v[100:101], v[100:101], v[10:11]
	v_pk_mul_f32 v[102:103], v[102:103], v[12:13]
	v_pk_mul_f32 v[10:11], v[72:73], v[40:41] op_sel_hi:[1,0]
	v_pk_mul_f32 v[12:13], v[74:75], v[40:41] op_sel_hi:[1,0]
	v_pk_mul_f32 v[104:105], v[104:105], v[10:11]
	v_pk_mul_f32 v[106:107], v[106:107], v[12:13]
	v_pk_mul_f32 v[10:11], v[76:77], v[40:41] op_sel_hi:[1,0]
	v_pk_mul_f32 v[12:13], v[78:79], v[40:41] op_sel_hi:[1,0]
	v_pk_mul_f32 v[108:109], v[108:109], v[10:11]
	v_pk_mul_f32 v[110:111], v[110:111], v[12:13]
	global_store_dwordx4 v2, v[80:83], s[40:41]
	global_store_dwordx4 v2, v[84:87], s[40:41] offset:1024
	global_store_dwordx4 v2, v[88:91], s[40:41] offset:2048
	global_store_dwordx4 v2, v[92:95], s[40:41] offset:3072
	global_store_dwordx4 v2, v[96:99], s[42:43]
	global_store_dwordx4 v2, v[100:103], s[42:43] offset:1024
	global_store_dwordx4 v2, v[104:107], s[42:43] offset:2048
	global_store_dwordx4 v2, v[108:111], s[42:43] offset:3072
	s_waitcnt vmcnt(26)
; __device__ __forceinline__ void final_norm(unsigned char* ws, int wv_) {
;     ...
;   for (int row = bidx() * 8 + wave; row < T_; row += gridDim.x * 8) {
;     float s = rsqrtf(ss[row] * (1.f / D_) + 1e-6f);
;     for (int i = 0; i < 8; ++i) {
;       int col = (i * 64 + lane) * 4;
;       float4 v = *(float4*)(x + (size_t)row * D_ + col);
;       float4 gg = *(const float4*)(g + col);
;       v.x *= s * gg.x; v.y *= s * gg.y; v.z *= s * gg.z; v.w *= s * gg.w;
;       *(float4*)(x + (size_t)row * D_ + col) = v;
;     }
	v_fmamk_f32 v7, v25, 0x3a000000, v22
	v_mul_f32_e32 v8, 0x4b800000, v7
	v_cmp_gt_f32_e32 vcc, s16, v7
	s_nop 1
	v_cndmask_b32_e32 v7, v7, v8, vcc
	v_rsq_f32_e32 v7, v7
	s_nop 0
	v_mul_f32_e32 v8, 0x45800000, v7
	v_cndmask_b32_e32 v40, v7, v8, vcc
	s_nop 0
	v_pk_mul_f32 v[10:11], v[48:49], v[40:41] op_sel_hi:[1,0]
	v_pk_mul_f32 v[12:13], v[50:51], v[40:41] op_sel_hi:[1,0]
	v_pk_mul_f32 v[112:113], v[112:113], v[10:11]
	v_pk_mul_f32 v[114:115], v[114:115], v[12:13]
	v_pk_mul_f32 v[10:11], v[52:53], v[40:41] op_sel_hi:[1,0]
	v_pk_mul_f32 v[12:13], v[54:55], v[40:41] op_sel_hi:[1,0]
	v_pk_mul_f32 v[116:117], v[116:117], v[10:11]
	v_pk_mul_f32 v[118:119], v[118:119], v[12:13]
	v_pk_mul_f32 v[10:11], v[56:57], v[40:41] op_sel_hi:[1,0]
	v_pk_mul_f32 v[12:13], v[58:59], v[40:41] op_sel_hi:[1,0]
	v_pk_mul_f32 v[120:121], v[120:121], v[10:11]
	v_pk_mul_f32 v[122:123], v[122:123], v[12:13]
	v_pk_mul_f32 v[10:11], v[60:61], v[40:41] op_sel_hi:[1,0]
	v_pk_mul_f32 v[12:13], v[62:63], v[40:41] op_sel_hi:[1,0]
	v_pk_mul_f32 v[124:125], v[124:125], v[10:11]
	v_pk_mul_f32 v[126:127], v[126:127], v[12:13]
	v_pk_mul_f32 v[10:11], v[64:65], v[40:41] op_sel_hi:[1,0]
	v_pk_mul_f32 v[12:13], v[66:67], v[40:41] op_sel_hi:[1,0]
	v_pk_mul_f32 v[128:129], v[128:129], v[10:11]
	v_pk_mul_f32 v[130:131], v[130:131], v[12:13]
	v_pk_mul_f32 v[10:11], v[68:69], v[40:41] op_sel_hi:[1,0]
	v_pk_mul_f32 v[12:13], v[70:71], v[40:41] op_sel_hi:[1,0]
	v_pk_mul_f32 v[132:133], v[132:133], v[10:11]
	v_pk_mul_f32 v[134:135], v[134:135], v[12:13]
	v_pk_mul_f32 v[10:11], v[72:73], v[40:41] op_sel_hi:[1,0]
	v_pk_mul_f32 v[12:13], v[74:75], v[40:41] op_sel_hi:[1,0]
	v_pk_mul_f32 v[136:137], v[136:137], v[10:11]
	v_pk_mul_f32 v[138:139], v[138:139], v[12:13]
	v_pk_mul_f32 v[10:11], v[76:77], v[40:41] op_sel_hi:[1,0]
	v_pk_mul_f32 v[12:13], v[78:79], v[40:41] op_sel_hi:[1,0]
	v_pk_mul_f32 v[140:141], v[140:141], v[10:11]
	v_pk_mul_f32 v[142:143], v[142:143], v[12:13]
	global_store_dwordx4 v2, v[112:115], s[44:45]
	global_store_dwordx4 v2, v[116:119], s[44:45] offset:1024
	global_store_dwordx4 v2, v[120:123], s[44:45] offset:2048
	global_store_dwordx4 v2, v[124:127], s[44:45] offset:3072
	global_store_dwordx4 v2, v[128:131], s[46:47]
	global_store_dwordx4 v2, v[132:135], s[46:47] offset:1024
	global_store_dwordx4 v2, v[136:139], s[46:47] offset:2048
	global_store_dwordx4 v2, v[140:143], s[46:47] offset:3072
	s_waitcnt vmcnt(25)
; __device__ __forceinline__ void final_norm(unsigned char* ws, int wv_) {
;     ...
;   for (int row = bidx() * 8 + wave; row < T_; row += gridDim.x * 8) {
;     float s = rsqrtf(ss[row] * (1.f / D_) + 1e-6f);
;     for (int i = 0; i < 8; ++i) {
;       int col = (i * 64 + lane) * 4;
;       float4 v = *(float4*)(x + (size_t)row * D_ + col);
;       float4 gg = *(const float4*)(g + col);
;       v.x *= s * gg.x; v.y *= s * gg.y; v.z *= s * gg.z; v.w *= s * gg.w;
;       *(float4*)(x + (size_t)row * D_ + col) = v;
;     }
	v_fmamk_f32 v7, v26, 0x3a000000, v22
	v_mul_f32_e32 v8, 0x4b800000, v7
	v_cmp_gt_f32_e32 vcc, s16, v7
	s_nop 1
	v_cndmask_b32_e32 v7, v7, v8, vcc
	v_rsq_f32_e32 v7, v7
	s_nop 0
	v_mul_f32_e32 v8, 0x45800000, v7
	v_cndmask_b32_e32 v40, v7, v8, vcc
	s_nop 0
	v_pk_mul_f32 v[10:11], v[48:49], v[40:41] op_sel_hi:[1,0]
	v_pk_mul_f32 v[12:13], v[50:51], v[40:41] op_sel_hi:[1,0]
	v_pk_mul_f32 v[144:145], v[144:145], v[10:11]
	v_pk_mul_f32 v[146:147], v[146:147], v[12:13]
	v_pk_mul_f32 v[10:11], v[52:53], v[40:41] op_sel_hi:[1,0]
	v_pk_mul_f32 v[12:13], v[54:55], v[40:41] op_sel_hi:[1,0]
	v_pk_mul_f32 v[148:149], v[148:149], v[10:11]
	v_pk_mul_f32 v[150:151], v[150:151], v[12:13]
	v_pk_mul_f32 v[10:11], v[56:57], v[40:41] op_sel_hi:[1,0]
	v_pk_mul_f32 v[12:13], v[58:59], v[40:41] op_sel_hi:[1,0]
	v_pk_mul_f32 v[152:153], v[152:153], v[10:11]
	v_pk_mul_f32 v[154:155], v[154:155], v[12:13]
	v_pk_mul_f32 v[10:11], v[60:61], v[40:41] op_sel_hi:[1,0]
	v_pk_mul_f32 v[12:13], v[62:63], v[40:41] op_sel_hi:[1,0]
	v_pk_mul_f32 v[156:157], v[156:157], v[10:11]
	v_pk_mul_f32 v[158:159], v[158:159], v[12:13]
	v_pk_mul_f32 v[10:11], v[64:65], v[40:41] op_sel_hi:[1,0]
	v_pk_mul_f32 v[12:13], v[66:67], v[40:41] op_sel_hi:[1,0]
	v_pk_mul_f32 v[160:161], v[160:161], v[10:11]
	v_pk_mul_f32 v[162:163], v[162:163], v[12:13]
	v_pk_mul_f32 v[10:11], v[68:69], v[40:41] op_sel_hi:[1,0]
	v_pk_mul_f32 v[12:13], v[70:71], v[40:41] op_sel_hi:[1,0]
	v_pk_mul_f32 v[164:165], v[164:165], v[10:11]
	v_pk_mul_f32 v[166:167], v[166:167], v[12:13]
	v_pk_mul_f32 v[10:11], v[72:73], v[40:41] op_sel_hi:[1,0]
	v_pk_mul_f32 v[12:13], v[74:75], v[40:41] op_sel_hi:[1,0]
	v_pk_mul_f32 v[168:169], v[168:169], v[10:11]
	v_pk_mul_f32 v[170:171], v[170:171], v[12:13]
	v_pk_mul_f32 v[10:11], v[76:77], v[40:41] op_sel_hi:[1,0]
	v_pk_mul_f32 v[12:13], v[78:79], v[40:41] op_sel_hi:[1,0]
	v_pk_mul_f32 v[172:173], v[172:173], v[10:11]
	v_pk_mul_f32 v[174:175], v[174:175], v[12:13]
	global_store_dwordx4 v2, v[144:147], s[48:49]
	global_store_dwordx4 v2, v[148:151], s[48:49] offset:1024
	global_store_dwordx4 v2, v[152:155], s[48:49] offset:2048
	global_store_dwordx4 v2, v[156:159], s[48:49] offset:3072
	global_store_dwordx4 v2, v[160:163], s[50:51]
	global_store_dwordx4 v2, v[164:167], s[50:51] offset:1024
	global_store_dwordx4 v2, v[168:171], s[50:51] offset:2048
	global_store_dwordx4 v2, v[172:175], s[50:51] offset:3072
	s_waitcnt vmcnt(24)
	v_fmamk_f32 v7, v27, 0x3a000000, v22
	v_mul_f32_e32 v8, 0x4b800000, v7
	v_cmp_gt_f32_e32 vcc, s16, v7
	s_nop 1
	v_cndmask_b32_e32 v7, v7, v8, vcc
	v_rsq_f32_e32 v7, v7
	s_nop 0
	v_mul_f32_e32 v8, 0x45800000, v7
	v_cndmask_b32_e32 v40, v7, v8, vcc
	s_nop 0
	v_pk_mul_f32 v[10:11], v[48:49], v[40:41] op_sel_hi:[1,0]
	v_pk_mul_f32 v[12:13], v[50:51], v[40:41] op_sel_hi:[1,0]
	v_pk_mul_f32 v[176:177], v[176:177], v[10:11]
	v_pk_mul_f32 v[178:179], v[178:179], v[12:13]
	v_pk_mul_f32 v[10:11], v[52:53], v[40:41] op_sel_hi:[1,0]
	v_pk_mul_f32 v[12:13], v[54:55], v[40:41] op_sel_hi:[1,0]
	v_pk_mul_f32 v[180:181], v[180:181], v[10:11]
	v_pk_mul_f32 v[182:183], v[182:183], v[12:13]
	v_pk_mul_f32 v[10:11], v[56:57], v[40:41] op_sel_hi:[1,0]
	v_pk_mul_f32 v[12:13], v[58:59], v[40:41] op_sel_hi:[1,0]
	v_pk_mul_f32 v[184:185], v[184:185], v[10:11]
	v_pk_mul_f32 v[186:187], v[186:187], v[12:13]
	v_pk_mul_f32 v[10:11], v[60:61], v[40:41] op_sel_hi:[1,0]
	v_pk_mul_f32 v[12:13], v[62:63], v[40:41] op_sel_hi:[1,0]
	v_pk_mul_f32 v[188:189], v[188:189], v[10:11]
	v_pk_mul_f32 v[190:191], v[190:191], v[12:13]
	v_pk_mul_f32 v[10:11], v[64:65], v[40:41] op_sel_hi:[1,0]
	v_pk_mul_f32 v[12:13], v[66:67], v[40:41] op_sel_hi:[1,0]
	v_pk_mul_f32 v[192:193], v[192:193], v[10:11]
	v_pk_mul_f32 v[194:195], v[194:195], v[12:13]
	v_pk_mul_f32 v[10:11], v[68:69], v[40:41] op_sel_hi:[1,0]
	v_pk_mul_f32 v[12:13], v[70:71], v[40:41] op_sel_hi:[1,0]
	v_pk_mul_f32 v[196:197], v[196:197], v[10:11]
	v_pk_mul_f32 v[198:199], v[198:199], v[12:13]
	v_pk_mul_f32 v[10:11], v[72:73], v[40:41] op_sel_hi:[1,0]
	v_pk_mul_f32 v[12:13], v[74:75], v[40:41] op_sel_hi:[1,0]
	v_pk_mul_f32 v[200:201], v[200:201], v[10:11]
	v_pk_mul_f32 v[202:203], v[202:203], v[12:13]
	v_pk_mul_f32 v[10:11], v[76:77], v[40:41] op_sel_hi:[1,0]
	v_pk_mul_f32 v[12:13], v[78:79], v[40:41] op_sel_hi:[1,0]
	v_pk_mul_f32 v[204:205], v[204:205], v[10:11]
	v_pk_mul_f32 v[206:207], v[206:207], v[12:13]
	global_store_dwordx4 v2, v[176:179], s[52:53]
	global_store_dwordx4 v2, v[180:183], s[52:53] offset:1024
	global_store_dwordx4 v2, v[184:187], s[52:53] offset:2048
	global_store_dwordx4 v2, v[188:191], s[52:53] offset:3072
	global_store_dwordx4 v2, v[192:195], s[54:55]
	global_store_dwordx4 v2, v[196:199], s[54:55] offset:1024
	global_store_dwordx4 v2, v[200:203], s[54:55] offset:2048
	global_store_dwordx4 v2, v[204:207], s[54:55] offset:3072
	s_branch .LBB0_1554
